# kv-split attention units: one static s_setprio 1 for waves 0-3 (key half 0) for the duration of the unit
# speedup vs baseline: 1.0423x; 1.0067x over previous
; #define WAIT_BAR(N) asm volatile("s_waitcnt vmcnt(" #N ") lgkmcnt(0)\n\ts_barrier":::"memory")
;   #define DMA_K(t,slot) glds16(ksrc+(long)(t)*KVBLK*PITCH,(unsigned)__builtin_amdgcn_readfirstlane(kdst+(slot)))
; template<int MODE,int THRL,bool NOMAX> __device__ __forceinline__ void attn_unit(const bf16*Qs,const bf16*__restrict__ Ks,const bf16*__restrict__ Vs,bf16*Os,int S,int q0,float sink2,float slope2,float*ssq,char*shm,int tid_in){
;     ...
;   const bf16*Qw=Qs+(long)(q0+wid*QBLK)*PITCH;
;   const bf16*Kh=Ks+(long)kt0*KVBLK*PITCH,*Vh=Vs+(long)kt0*KVBLK*PITCH;
;   const unsigned lds0=(unsigned)(uintptr_t)shm;
;   float*wsf=(float*)(shm+LDS_WS)+wid*64;
;   const bf16*ksrc=Kh+(long)lane*PITCH+wid*8;
;   const bf16*vsrc=Vh+(long)(16*(wid&3)+(lane>>2))*PITCH+(wid>>2)*32+(lane&3)*8;
;   const unsigned kdst=lds0+LDS_K+wid*1024, vdst=lds0+LDS_V+wid*1024;
;     ...
;   const int vb0=(int)(lds0+LDS_V)+((lane>>4)&1)*32+(lane&3)*8+(4*hi+((lane&15)>>2))*64;
;   const char*Kbase=shm+LDS_K; bf16x8 kf[8];
;   const lds_cptr shm3=(lds_cptr)shm; const lds_cptr kp0=shm3+LDS_K+hi*1024+r32*16; const lds_cptr vp0=shm3+LDS_V+((lane>>4)&1)*32+(lane&3)*8+(4*hi+((lane&15)>>2))*64;
;   const int NT=kend-kt0;
;   DMA_K(0,0);DMA_V(0,0);DMA_K(1,SLOTB);
;   bf16x8 qr[4];
;   #pragma unroll
;   for(int d0=0;d0<4;++d0)qr[d0]=*reinterpret_cast<const bf16x8*>(&Qw[(long)r32*PITCH+d0*16+hi*8]);
;   float mhat=0.f,l_reg=0.f;f32x16 o[2];o[0]=f32x16{};o[1]=f32x16{};f32x16 negm=f32x16{};
;   if(MODE==1){ mhat=sink2; l_reg=(hi==0)?1.f:0.f;
;     #pragma unroll
;     for(int r=0;r<16;++r)negm[r]=-sink2; }
;   if(!NOMAX)asm volatile("":"+v"(negm));
;   f32x16 lsum=f32x16{}; bf16x8 onesv;
;   #pragma unroll
;   for(int i_=0;i_<8;++i_)onesv[i_]=(short)0x3F80;
;   asm volatile("":"+v"(onesv));
;   const int qrel=wid*QBLK+r32;
;   const int qk0=q0+qrel-kt0*KVBLK-4*hi;
;     ...
;   bool resc=false;
;     ...
;   f32x16 pA0,pA1,pB0,pB1;
;   int sl_prev=0,sl_cur=0,sl_next=SLOTB,sl_n2=2*SLOTB;
;     ...
;   DMA_K(2,2*SLOTB);DMA_K(3,3*SLOTB);DMA_V(1,SLOTB);
;   WAIT_BAR(5);
;   qkt(pA0,pA1,Kbase,qr,(NOMAX?f32x16{}:negm),r32,hi);asm volatile("s_nop 15\n\ts_nop 7":"+v"(pA0),"+v"(pA1));CMASK(pA0,pA1,0);
;   START(pA0,pA1);
;   _Pragma("unroll") for(int r=0;r<16;++r)pA1[r]=__builtin_amdgcn_exp2f(pA1[r]);
;   WAIT_BAR(2);
;   DMA_K(4,4*SLOTB);DMA_V(2,2*SLOTB);
;   ROT();
;   kload8(kf,kp0+sl_cur);
.LBB0_549:
	s_and_b64 vcc, exec, s[4:5]
	s_cbranch_vccz .LBB0_389
	s_waitcnt lgkmcnt(0)
	v_readfirstlane_b32 s31, v251
	v_and_b32_e32 v129, 63, v251
	v_and_b32_e32 v0, 31, v251
	s_lshr_b32 s30, s31, 6
	s_and_b32 s5, s30, 3
	s_lshr_b32 s57, s30, 2
	s_lshl_b32 s4, s5, 6
	s_add_i32 s4, s4, s51
	s_lshr_b32 s40, s50, 6
	s_cmp_eq_u32 s57, 0
	s_cbranch_scc0 .Lkvs_noprio
	s_setprio 1
.Lkvs_noprio:
	v_mul_u32_u24_e32 v214, 0xc00, v129
	s_lshl_b32 s10, s30, 4
	v_add_u32_e32 v214, s10, v214
	v_lshrrev_b32_e32 v215, 2, v129
	s_lshl_b32 s10, s5, 4
	v_add_u32_e32 v215, s10, v215
	v_mul_u32_u24_e32 v215, 0xc00, v215
	v_and_b32_e32 v217, 3, v129
	v_lshlrev_b32_e32 v217, 4, v217
	s_lshl_b32 s10, s57, 6
	v_add3_u32 v215, v215, v217, s10
	s_add_u32 s28, s28, 0x400
	s_addc_u32 s29, s29, 0
	s_add_u32 s36, s28, 0x100
	s_addc_u32 s37, s29, 0
	s_lshl_b32 s38, s30, 10
	s_add_i32 s39, s38, 0xa000
	v_lshrrev_b32_e32 v202, 5, v129
	v_lshlrev_b32_e32 v202, 10, v202
	v_lshl_add_u32 v202, v0, 4, v202
	s_lshl_b32 s10, s57, 9
	v_add_u32_e32 v202, s10, v202
	v_lshlrev_b32_e32 v217, 1, v129
	v_and_b32_e32 v217, 32, v217
	v_and_b32_e32 v126, 3, v129
	v_lshl_add_u32 v217, v126, 3, v217
	v_lshlrev_b32_e32 v126, 4, v129
	v_and_b32_e32 v126, 0xc0, v126
	v_lshrrev_b32_e32 v127, 5, v129
	v_lshl_or_b32 v126, v127, 8, v126
	s_lshl_b32 s10, s57, 11
	v_add3_u32 v217, v217, v126, s10
	s_mul_i32 s10, s4, 0xc00
	s_mul_hi_i32 s11, s4, 0xc00
	s_add_u32 s10, s52, s10
	s_addc_u32 s11, s53, s11
	s_add_u32 s14, s10, 0x18000
	s_addc_u32 s15, s11, 0
	v_mul_u32_u24_e32 v126, 0xc00, v0
	v_lshl_or_b32 v126, v127, 4, v126
	s_mov_b32 m0, s38
	s_nop 0
	global_load_lds_dwordx4 v214, s[28:29]
	s_mov_b32 m0, s39
	s_nop 0
	global_load_lds_dwordx4 v215, s[36:37]
	s_add_u32 s28, s28, 0x30000
	s_addc_u32 s29, s29, 0
	s_add_i32 m0, s38, 0x2000
	s_nop 0
	global_load_lds_dwordx4 v214, s[28:29]
	global_load_dwordx4 v[146:149], v126, s[10:11]
	global_load_dwordx4 v[150:153], v126, s[10:11] offset:32
	global_load_dwordx4 v[154:157], v126, s[10:11] offset:64
	global_load_dwordx4 v[158:161], v126, s[10:11] offset:96
	global_load_dwordx4 v[162:165], v126, s[14:15]
	global_load_dwordx4 v[166:169], v126, s[14:15] offset:32
	global_load_dwordx4 v[170:173], v126, s[14:15] offset:64
	global_load_dwordx4 v[174:177], v126, s[14:15] offset:96
	s_add_u32 s28, s28, 0x30000
	s_addc_u32 s29, s29, 0
	s_add_i32 m0, s38, 0x4000
	s_nop 0
	global_load_lds_dwordx4 v214, s[28:29]
	s_add_u32 s28, s28, 0x30000
	s_addc_u32 s29, s29, 0
	s_add_i32 m0, s38, 0x6000
	s_nop 0
	global_load_lds_dwordx4 v214, s[28:29]
	s_add_u32 s36, s36, 0x30000
	s_addc_u32 s37, s37, 0
	s_add_i32 m0, s39, 0x2000
	s_nop 0
	global_load_lds_dwordx4 v215, s[36:37]
	s_add_u32 s28, s28, 0x30000
	s_addc_u32 s29, s29, 0
	s_add_u32 s36, s36, 0x30000
	s_addc_u32 s37, s37, 0
	v_mov_b32_e32 v126, 0
	v_mov_b32_e32 v127, 0
	v_mov_b32_e32 v2, 0
	v_mov_b32_e32 v3, 0
	v_mov_b32_e32 v4, 0
	v_mov_b32_e32 v5, 0
	v_mov_b32_e32 v6, 0
	v_mov_b32_e32 v7, 0
	v_mov_b32_e32 v8, 0
	v_mov_b32_e32 v9, 0
	v_mov_b32_e32 v10, 0
	v_mov_b32_e32 v11, 0
	v_mov_b32_e32 v12, 0
	v_mov_b32_e32 v13, 0
	v_mov_b32_e32 v14, 0
	v_mov_b32_e32 v15, 0
	v_mov_b32_e32 v16, 0
	v_mov_b32_e32 v17, 0
	v_mov_b32_e32 v18, 0
	v_mov_b32_e32 v19, 0
	v_mov_b32_e32 v20, 0
	v_mov_b32_e32 v21, 0
	v_mov_b32_e32 v22, 0
	v_mov_b32_e32 v23, 0
	v_mov_b32_e32 v24, 0
	v_mov_b32_e32 v25, 0
	v_mov_b32_e32 v26, 0
	v_mov_b32_e32 v27, 0
	v_mov_b32_e32 v28, 0
	v_mov_b32_e32 v29, 0
	v_mov_b32_e32 v30, 0
	v_mov_b32_e32 v31, 0
	v_mov_b32_e32 v32, 0
	v_mov_b32_e32 v33, 0
	v_mov_b32_e32 v34, 0
	v_mov_b32_e32 v35, 0
	v_mov_b32_e32 v36, 0
	v_mov_b32_e32 v37, 0
	v_mov_b32_e32 v38, 0
	v_mov_b32_e32 v39, 0
	v_mov_b32_e32 v40, 0
	v_mov_b32_e32 v41, 0
	v_mov_b32_e32 v42, 0
	v_mov_b32_e32 v43, 0
	v_mov_b32_e32 v44, 0
	v_mov_b32_e32 v45, 0
	v_mov_b32_e32 v46, 0
	v_mov_b32_e32 v47, 0
	v_mov_b32_e32 v48, 0
	v_mov_b32_e32 v49, 0
	v_mov_b32_e32 v50, 0
	v_mov_b32_e32 v51, 0
	v_mov_b32_e32 v52, 0
	v_mov_b32_e32 v53, 0
	v_mov_b32_e32 v54, 0
	v_mov_b32_e32 v55, 0
	v_mov_b32_e32 v56, 0
	v_mov_b32_e32 v57, 0
	v_mov_b32_e32 v58, 0
	v_mov_b32_e32 v59, 0
	v_mov_b32_e32 v60, 0
	v_mov_b32_e32 v61, 0
	v_mov_b32_e32 v62, 0
	v_mov_b32_e32 v63, 0
	v_mov_b32_e32 v64, 0
	v_mov_b32_e32 v65, 0
	s_waitcnt vmcnt(3)
	s_barrier
	ds_read_b128 v[178:181], v202
	ds_read_b128 v[182:185], v202 offset:2048
	ds_read_b128 v[186:189], v202 offset:4096
	ds_read_b128 v[114:117], v202 offset:6144
	s_waitcnt lgkmcnt(0)
	v_mfma_f32_32x32x16_bf16 v[66:81], v[178:181], v[146:149], 0
	v_mfma_f32_32x32x16_bf16 v[82:97], v[178:181], v[162:165], 0
	v_mfma_f32_32x32x16_bf16 v[66:81], v[182:185], v[150:153], v[66:81]
	v_mfma_f32_32x32x16_bf16 v[82:97], v[182:185], v[166:169], v[82:97]
	v_mfma_f32_32x32x16_bf16 v[66:81], v[186:189], v[154:157], v[66:81]
	v_mfma_f32_32x32x16_bf16 v[82:97], v[186:189], v[170:173], v[82:97]
	v_mfma_f32_32x32x16_bf16 v[66:81], v[114:117], v[158:161], v[66:81]
	v_mfma_f32_32x32x16_bf16 v[82:97], v[114:117], v[174:177], v[82:97]
	s_nop 15
	s_nop 7
	v_exp_f32_e32 v66, v66
	v_exp_f32_e32 v67, v67
	v_exp_f32_e32 v68, v68
	v_exp_f32_e32 v69, v69
	v_exp_f32_e32 v70, v70
	v_exp_f32_e32 v71, v71
	v_exp_f32_e32 v72, v72
	v_exp_f32_e32 v73, v73
	v_exp_f32_e32 v74, v74
	v_exp_f32_e32 v75, v75
	v_exp_f32_e32 v76, v76
	v_exp_f32_e32 v77, v77
	v_exp_f32_e32 v78, v78
	v_exp_f32_e32 v79, v79
	v_exp_f32_e32 v80, v80
	v_exp_f32_e32 v81, v81
	v_exp_f32_e32 v82, v82
	v_exp_f32_e32 v83, v83
	v_exp_f32_e32 v84, v84
	v_exp_f32_e32 v85, v85
	v_exp_f32_e32 v86, v86
	v_exp_f32_e32 v87, v87
	v_exp_f32_e32 v88, v88
	v_exp_f32_e32 v89, v89
	v_exp_f32_e32 v90, v90
	v_exp_f32_e32 v91, v91
	v_exp_f32_e32 v92, v92
	v_exp_f32_e32 v93, v93
	v_exp_f32_e32 v94, v94
	v_exp_f32_e32 v95, v95
	v_exp_f32_e32 v96, v96
	v_exp_f32_e32 v97, v97
	s_waitcnt vmcnt(0) lgkmcnt(0)
	s_barrier
	s_add_i32 m0, s38, 0x8000
	s_nop 0
	global_load_lds_dwordx4 v214, s[28:29]
	s_add_i32 m0, s39, 0x4000
	s_nop 0
	global_load_lds_dwordx4 v215, s[36:37]
	s_add_u32 s28, s28, 0x30000
	s_addc_u32 s29, s29, 0
	s_add_u32 s36, s36, 0x30000
	s_addc_u32 s37, s37, 0
	s_mov_b32 s15, 0
	s_movk_i32 s14, 0x2000
	s_movk_i32 s44, 0x4000
	s_movk_i32 s51, 0x6000
	v_add_u32_e32 v129, s14, v202
	ds_read_b128 v[178:181], v129
	ds_read_b128 v[182:185], v129 offset:2048
	ds_read_b128 v[186:189], v129 offset:4096
	ds_read_b128 v[114:117], v129 offset:6144
	s_mov_b32 s18, 1

; __device__ __forceinline__ void attn_phase(char* lds, const attn_body::bf16* P, attn_body::bf16* O, const float* sink, float* ssq, const float* gq, const float* gk, int vcu, int G, int tid_in) {
;     ...
;         if (mode == 0) { if (nomax) attn_body::attn_unit<0, 8, true>(Q, K, V, Oo, S, q0, 0.f, 0.f, sq, lds, tid_in); else attn_body::attn_unit<0, 8, false>(Q, K, V, Oo, S, q0, 0.f, 0.f, sq, lds, tid_in); }
;         else { const float sink2 = sink[hq] * LOG2E; const float slope2 = __builtin_amdgcn_exp2f(-(float)(hq + 1)) * LOG2E; attn_body::attn_unit<1, 8, false>(Q, K, V, Oo, S, q0, sink2, slope2, sq, lds, tid_in); }
;     }
.Lkvs_done:
	s_setprio 0
	s_mov_b64 s[10:11], exec
	s_branch .LBB0_388
